# rope-k prep job: four iterations unrolled, all sixteen loads issued first, counted waits
# speedup vs baseline: 1.0056x; 1.0017x over previous
.LBB0_723:
	v_mov_b32_e32 v79, v193
	v_add_u32_e32 v64, s10, v0
	v_add_u32_e32 v64, 0xfff10100, v64
	v_ashrrev_i32_e32 v76, 2, v64
	v_and_b32_e32 v66, 12, v1
	v_mov_b64_e32 v[64:65], s[14:15]
	v_mad_i64_i32 v[64:65], s[12:13], v76, s16, v[64:65]
	v_lshlrev_b32_e32 v78, 1, v66
	v_lshl_add_u64 v[64:65], v[64:65], 0, v[78:79]
	v_add_co_u32_e32 v64, vcc, 0x1000, v64
	v_lshlrev_b32_e32 v70, 2, v66
	s_nop 0
	v_addc_co_u32_e32 v65, vcc, 0, v65, vcc
	global_load_dwordx2 v[72:73], v[64:65], off offset:3072
	global_load_dwordx2 v[74:75], v[64:65], off offset:3104
	v_lshlrev_b32_e32 v64, 4, v76
	v_ashrrev_i32_e32 v65, 31, v64
	v_lshlrev_b64 v[68:69], 2, v[64:65]
	v_lshl_add_u64 v[64:65], s[24:25], 0, v[68:69]
	v_mov_b32_e32 v71, v79
	v_lshl_add_u64 v[68:69], s[26:27], 0, v[68:69]
	v_lshl_add_u64 v[64:65], v[64:65], 0, v[70:71]
	v_lshl_add_u64 v[68:69], v[68:69], 0, v[70:71]
	global_load_dwordx4 v[64:67], v[64:65], off
	global_load_dwordx4 v[68:71], v[68:69], off
	v_add_u32_e32 v0, 0x100, v0
	v_add_u32_e32 v1, 0x400, v1
	v_mov_b32_e32 v95, v193
	v_add_u32_e32 v80, s10, v0
	v_add_u32_e32 v80, 0xfff10100, v80
	v_ashrrev_i32_e32 v92, 2, v80
	v_and_b32_e32 v82, 12, v1
	v_mov_b64_e32 v[80:81], s[14:15]
	v_mad_i64_i32 v[80:81], s[12:13], v92, s16, v[80:81]
	v_lshlrev_b32_e32 v94, 1, v82
	v_lshl_add_u64 v[80:81], v[80:81], 0, v[94:95]
	v_add_co_u32_e32 v80, vcc, 0x1000, v80
	v_lshlrev_b32_e32 v86, 2, v82
	s_nop 0
	v_addc_co_u32_e32 v81, vcc, 0, v81, vcc
	global_load_dwordx2 v[88:89], v[80:81], off offset:3072
	global_load_dwordx2 v[90:91], v[80:81], off offset:3104
	v_lshlrev_b32_e32 v80, 4, v92
	v_ashrrev_i32_e32 v81, 31, v80
	v_lshlrev_b64 v[84:85], 2, v[80:81]
	v_lshl_add_u64 v[80:81], s[24:25], 0, v[84:85]
	v_mov_b32_e32 v87, v95
	v_lshl_add_u64 v[84:85], s[26:27], 0, v[84:85]
	v_lshl_add_u64 v[80:81], v[80:81], 0, v[86:87]
	v_lshl_add_u64 v[84:85], v[84:85], 0, v[86:87]
	global_load_dwordx4 v[80:83], v[80:81], off
	global_load_dwordx4 v[84:87], v[84:85], off
	v_add_u32_e32 v0, 0x100, v0
	v_add_u32_e32 v1, 0x400, v1
	v_mov_b32_e32 v111, v193
	v_add_u32_e32 v96, s10, v0
	v_add_u32_e32 v96, 0xfff10100, v96
	v_ashrrev_i32_e32 v108, 2, v96
	v_and_b32_e32 v98, 12, v1
	v_mov_b64_e32 v[96:97], s[14:15]
	v_mad_i64_i32 v[96:97], s[12:13], v108, s16, v[96:97]
	v_lshlrev_b32_e32 v110, 1, v98
	v_lshl_add_u64 v[96:97], v[96:97], 0, v[110:111]
	v_add_co_u32_e32 v96, vcc, 0x1000, v96
	v_lshlrev_b32_e32 v102, 2, v98
	s_nop 0
	v_addc_co_u32_e32 v97, vcc, 0, v97, vcc
	global_load_dwordx2 v[104:105], v[96:97], off offset:3072
	global_load_dwordx2 v[106:107], v[96:97], off offset:3104
	v_lshlrev_b32_e32 v96, 4, v108
	v_ashrrev_i32_e32 v97, 31, v96
	v_lshlrev_b64 v[100:101], 2, v[96:97]
	v_lshl_add_u64 v[96:97], s[24:25], 0, v[100:101]
	v_mov_b32_e32 v103, v111
	v_lshl_add_u64 v[100:101], s[26:27], 0, v[100:101]
	v_lshl_add_u64 v[96:97], v[96:97], 0, v[102:103]
	v_lshl_add_u64 v[100:101], v[100:101], 0, v[102:103]
	global_load_dwordx4 v[96:99], v[96:97], off
	global_load_dwordx4 v[100:103], v[100:101], off
	v_add_u32_e32 v0, 0x100, v0
	v_add_u32_e32 v1, 0x400, v1
	v_mov_b32_e32 v127, v193
	v_add_u32_e32 v112, s10, v0
	v_add_u32_e32 v112, 0xfff10100, v112
	v_ashrrev_i32_e32 v124, 2, v112
	v_and_b32_e32 v114, 12, v1
	v_mov_b64_e32 v[112:113], s[14:15]
	v_mad_i64_i32 v[112:113], s[12:13], v124, s16, v[112:113]
	v_lshlrev_b32_e32 v126, 1, v114
	v_lshl_add_u64 v[112:113], v[112:113], 0, v[126:127]
	v_add_co_u32_e32 v112, vcc, 0x1000, v112
	v_lshlrev_b32_e32 v118, 2, v114
	s_nop 0
	v_addc_co_u32_e32 v113, vcc, 0, v113, vcc
	global_load_dwordx2 v[120:121], v[112:113], off offset:3072
	global_load_dwordx2 v[122:123], v[112:113], off offset:3104
	v_lshlrev_b32_e32 v112, 4, v124
	v_ashrrev_i32_e32 v113, 31, v112
	v_lshlrev_b64 v[116:117], 2, v[112:113]
	v_lshl_add_u64 v[112:113], s[24:25], 0, v[116:117]
	v_mov_b32_e32 v119, v127
	v_lshl_add_u64 v[116:117], s[26:27], 0, v[116:117]
	v_lshl_add_u64 v[112:113], v[112:113], 0, v[118:119]
	v_lshl_add_u64 v[116:117], v[116:117], 0, v[118:119]
	global_load_dwordx4 v[112:115], v[112:113], off
	global_load_dwordx4 v[116:119], v[116:117], off
	v_add_u32_e32 v0, 0x100, v0
	v_add_u32_e32 v1, 0x400, v1
	s_mov_b32 s11, 0xbdd0000
	s_waitcnt vmcnt(12) lgkmcnt(0)
	v_lshlrev_b32_e32 v14, 16, v72
	v_lshlrev_b32_e32 v16, 16, v74
	v_and_b32_e32 v17, 0xffff0000, v74
	v_and_b32_e32 v15, 0xffff0000, v72
	v_lshlrev_b32_e32 v74, 16, v75
	v_and_b32_e32 v75, 0xffff0000, v75
	v_pk_mul_f32 v[18:19], v[68:69], v[16:17]
	s_nop 0
	v_pk_fma_f32 v[18:19], v[64:65], v[14:15], v[18:19] neg_lo:[0,0,1] neg_hi:[0,0,1]
	v_pk_mul_f32 v[64:65], v[64:65], v[16:17]
	v_cvt_pk_bf16_f32 v72, v18, v19
	v_pk_fma_f32 v[64:65], v[68:69], v[14:15], v[64:65]
	v_lshlrev_b32_e32 v68, 16, v73
	v_and_b32_e32 v69, 0xffff0000, v73
	v_pk_mul_f32 v[14:15], v[70:71], v[74:75]
	v_cvt_pk_bf16_f32 v64, v64, v65
	v_pk_fma_f32 v[14:15], v[66:67], v[68:69], v[14:15] neg_lo:[0,0,1] neg_hi:[0,0,1]
	v_pk_mul_f32 v[66:67], v[66:67], v[74:75]
	v_cvt_pk_bf16_f32 v73, v14, v15
	v_pk_fma_f32 v[66:67], v[70:71], v[68:69], v[66:67]
	s_nop 0
	v_cvt_pk_bf16_f32 v65, v66, v67
	v_mov_b64_e32 v[66:67], s[52:53]
	v_mad_i64_i32 v[66:67], s[12:13], v76, s17, v[66:67]
	v_lshl_add_u64 v[66:67], v[66:67], 0, v[78:79]
	s_mov_b64 s[12:13], 0xbdd0080
	v_add_co_u32_e32 v70, vcc, s11, v66
	v_lshl_add_u64 v[68:69], v[66:67], 0, s[12:13]
	s_nop 0
	v_addc_co_u32_e32 v71, vcc, 0, v67, vcc
	s_mov_b64 s[12:13], 0xbdd0140
	global_store_dwordx2 v[70:71], v[72:73], off offset:128
	global_store_dwordx2 v[68:69], v[64:65], off offset:32
	v_lshl_add_u64 v[68:69], v[66:67], 0, s[12:13]
	s_mov_b64 s[12:13], 0xbdd0200
	global_store_dwordx2 v[70:71], v[72:73], off offset:320
	global_store_dwordx2 v[68:69], v[64:65], off offset:32
	v_lshl_add_u64 v[68:69], v[66:67], 0, s[12:13]
	s_mov_b64 s[12:13], 0xbdd02c0
	global_store_dwordx2 v[70:71], v[72:73], off offset:512
	global_store_dwordx2 v[68:69], v[64:65], off offset:32
	v_lshl_add_u64 v[66:67], v[66:67], 0, s[12:13]
	global_store_dwordx2 v[70:71], v[72:73], off offset:704
	global_store_dwordx2 v[66:67], v[64:65], off offset:32
	s_mov_b32 s11, 0xbdd0000
	s_waitcnt vmcnt(16) lgkmcnt(0)
	v_lshlrev_b32_e32 v14, 16, v88
	v_lshlrev_b32_e32 v16, 16, v90
	v_and_b32_e32 v17, 0xffff0000, v90
	v_and_b32_e32 v15, 0xffff0000, v88
	v_lshlrev_b32_e32 v90, 16, v91
	v_and_b32_e32 v91, 0xffff0000, v91
	v_pk_mul_f32 v[18:19], v[84:85], v[16:17]
	s_nop 0
	v_pk_fma_f32 v[18:19], v[80:81], v[14:15], v[18:19] neg_lo:[0,0,1] neg_hi:[0,0,1]
	v_pk_mul_f32 v[80:81], v[80:81], v[16:17]
	v_cvt_pk_bf16_f32 v88, v18, v19
	v_pk_fma_f32 v[80:81], v[84:85], v[14:15], v[80:81]
	v_lshlrev_b32_e32 v84, 16, v89
	v_and_b32_e32 v85, 0xffff0000, v89
	v_pk_mul_f32 v[14:15], v[86:87], v[90:91]
	v_cvt_pk_bf16_f32 v80, v80, v81
	v_pk_fma_f32 v[14:15], v[82:83], v[84:85], v[14:15] neg_lo:[0,0,1] neg_hi:[0,0,1]
	v_pk_mul_f32 v[82:83], v[82:83], v[90:91]
	v_cvt_pk_bf16_f32 v89, v14, v15
	v_pk_fma_f32 v[82:83], v[86:87], v[84:85], v[82:83]
	s_nop 0
	v_cvt_pk_bf16_f32 v81, v82, v83
	v_mov_b64_e32 v[82:83], s[52:53]
	v_mad_i64_i32 v[82:83], s[12:13], v92, s17, v[82:83]
	v_lshl_add_u64 v[82:83], v[82:83], 0, v[94:95]
	s_mov_b64 s[12:13], 0xbdd0080
	v_add_co_u32_e32 v86, vcc, s11, v82
	v_lshl_add_u64 v[84:85], v[82:83], 0, s[12:13]
	s_nop 0
	v_addc_co_u32_e32 v87, vcc, 0, v83, vcc
	s_mov_b64 s[12:13], 0xbdd0140
	global_store_dwordx2 v[86:87], v[88:89], off offset:128
	global_store_dwordx2 v[84:85], v[80:81], off offset:32
	v_lshl_add_u64 v[84:85], v[82:83], 0, s[12:13]
	s_mov_b64 s[12:13], 0xbdd0200
	global_store_dwordx2 v[86:87], v[88:89], off offset:320
	global_store_dwordx2 v[84:85], v[80:81], off offset:32
	v_lshl_add_u64 v[84:85], v[82:83], 0, s[12:13]
	s_mov_b64 s[12:13], 0xbdd02c0
	global_store_dwordx2 v[86:87], v[88:89], off offset:512
	global_store_dwordx2 v[84:85], v[80:81], off offset:32
	v_lshl_add_u64 v[82:83], v[82:83], 0, s[12:13]
	global_store_dwordx2 v[86:87], v[88:89], off offset:704
	global_store_dwordx2 v[82:83], v[80:81], off offset:32
	s_mov_b32 s11, 0xbdd0000
	s_waitcnt vmcnt(20) lgkmcnt(0)
	v_lshlrev_b32_e32 v14, 16, v104
	v_lshlrev_b32_e32 v16, 16, v106
	v_and_b32_e32 v17, 0xffff0000, v106
	v_and_b32_e32 v15, 0xffff0000, v104
	v_lshlrev_b32_e32 v106, 16, v107
	v_and_b32_e32 v107, 0xffff0000, v107
	v_pk_mul_f32 v[18:19], v[100:101], v[16:17]
	s_nop 0
	v_pk_fma_f32 v[18:19], v[96:97], v[14:15], v[18:19] neg_lo:[0,0,1] neg_hi:[0,0,1]
	v_pk_mul_f32 v[96:97], v[96:97], v[16:17]
	v_cvt_pk_bf16_f32 v104, v18, v19
	v_pk_fma_f32 v[96:97], v[100:101], v[14:15], v[96:97]
	v_lshlrev_b32_e32 v100, 16, v105
	v_and_b32_e32 v101, 0xffff0000, v105
	v_pk_mul_f32 v[14:15], v[102:103], v[106:107]
	v_cvt_pk_bf16_f32 v96, v96, v97
	v_pk_fma_f32 v[14:15], v[98:99], v[100:101], v[14:15] neg_lo:[0,0,1] neg_hi:[0,0,1]
	v_pk_mul_f32 v[98:99], v[98:99], v[106:107]
	v_cvt_pk_bf16_f32 v105, v14, v15
	v_pk_fma_f32 v[98:99], v[102:103], v[100:101], v[98:99]
	s_nop 0
	v_cvt_pk_bf16_f32 v97, v98, v99
	v_mov_b64_e32 v[98:99], s[52:53]
	v_mad_i64_i32 v[98:99], s[12:13], v108, s17, v[98:99]
	v_lshl_add_u64 v[98:99], v[98:99], 0, v[110:111]
	s_mov_b64 s[12:13], 0xbdd0080
	v_add_co_u32_e32 v102, vcc, s11, v98
	v_lshl_add_u64 v[100:101], v[98:99], 0, s[12:13]
	s_nop 0
	v_addc_co_u32_e32 v103, vcc, 0, v99, vcc
	s_mov_b64 s[12:13], 0xbdd0140
	global_store_dwordx2 v[102:103], v[104:105], off offset:128
	global_store_dwordx2 v[100:101], v[96:97], off offset:32
	v_lshl_add_u64 v[100:101], v[98:99], 0, s[12:13]
	s_mov_b64 s[12:13], 0xbdd0200
	global_store_dwordx2 v[102:103], v[104:105], off offset:320
	global_store_dwordx2 v[100:101], v[96:97], off offset:32
	v_lshl_add_u64 v[100:101], v[98:99], 0, s[12:13]
	s_mov_b64 s[12:13], 0xbdd02c0
	global_store_dwordx2 v[102:103], v[104:105], off offset:512
	global_store_dwordx2 v[100:101], v[96:97], off offset:32
	v_lshl_add_u64 v[98:99], v[98:99], 0, s[12:13]
	global_store_dwordx2 v[102:103], v[104:105], off offset:704
	global_store_dwordx2 v[98:99], v[96:97], off offset:32
	s_mov_b32 s11, 0xbdd0000
	s_waitcnt vmcnt(24) lgkmcnt(0)
	v_lshlrev_b32_e32 v14, 16, v120
	v_lshlrev_b32_e32 v16, 16, v122
	v_and_b32_e32 v17, 0xffff0000, v122
	v_and_b32_e32 v15, 0xffff0000, v120
	v_lshlrev_b32_e32 v122, 16, v123
	v_and_b32_e32 v123, 0xffff0000, v123
	v_pk_mul_f32 v[18:19], v[116:117], v[16:17]
	s_nop 0
	v_pk_fma_f32 v[18:19], v[112:113], v[14:15], v[18:19] neg_lo:[0,0,1] neg_hi:[0,0,1]
	v_pk_mul_f32 v[112:113], v[112:113], v[16:17]
	v_cvt_pk_bf16_f32 v120, v18, v19
	v_pk_fma_f32 v[112:113], v[116:117], v[14:15], v[112:113]
	v_lshlrev_b32_e32 v116, 16, v121
	v_and_b32_e32 v117, 0xffff0000, v121
	v_pk_mul_f32 v[14:15], v[118:119], v[122:123]
	v_cvt_pk_bf16_f32 v112, v112, v113
	v_pk_fma_f32 v[14:15], v[114:115], v[116:117], v[14:15] neg_lo:[0,0,1] neg_hi:[0,0,1]
	v_pk_mul_f32 v[114:115], v[114:115], v[122:123]
	v_cvt_pk_bf16_f32 v121, v14, v15
	v_pk_fma_f32 v[114:115], v[118:119], v[116:117], v[114:115]
	s_nop 0
	v_cvt_pk_bf16_f32 v113, v114, v115
	v_mov_b64_e32 v[114:115], s[52:53]
	v_mad_i64_i32 v[114:115], s[12:13], v124, s17, v[114:115]
	v_lshl_add_u64 v[114:115], v[114:115], 0, v[126:127]
	s_mov_b64 s[12:13], 0xbdd0080
	v_add_co_u32_e32 v118, vcc, s11, v114
	v_lshl_add_u64 v[116:117], v[114:115], 0, s[12:13]
	s_nop 0
	v_addc_co_u32_e32 v119, vcc, 0, v115, vcc
	s_mov_b64 s[12:13], 0xbdd0140
	global_store_dwordx2 v[118:119], v[120:121], off offset:128
	global_store_dwordx2 v[116:117], v[112:113], off offset:32
	v_lshl_add_u64 v[116:117], v[114:115], 0, s[12:13]
	s_mov_b64 s[12:13], 0xbdd0200
	global_store_dwordx2 v[118:119], v[120:121], off offset:320
	global_store_dwordx2 v[116:117], v[112:113], off offset:32
	v_lshl_add_u64 v[116:117], v[114:115], 0, s[12:13]
	s_mov_b64 s[12:13], 0xbdd02c0
	global_store_dwordx2 v[118:119], v[120:121], off offset:512
	global_store_dwordx2 v[116:117], v[112:113], off offset:32
	v_lshl_add_u64 v[114:115], v[114:115], 0, s[12:13]
	global_store_dwordx2 v[118:119], v[120:121], off offset:704
	global_store_dwordx2 v[114:115], v[112:113], off offset:32
